# DF early half (waves 0-3): one static priority raise for its whole key loop (7.4 mirrored: raising the late half loses 7 us, raising the early half wins)
# speedup vs baseline: 1.0052x; 1.0052x over previous
.LBB0_424:
	s_and_b64 vcc, exec, s[2:3]
	s_cbranch_vccz .LBB0_451
	s_setprio 1
	s_mov_b32 s2, m0
	s_mov_b32 m0, s76
	s_nop 0
	global_load_lds_dwordx4 v[200:201], off
	s_mov_b32 m0, s2
	v_readlane_b32 s3, v255, 15
	s_mov_b32 s2, m0
	s_mov_b32 m0, s3
	s_nop 0
	global_load_lds_dwordx4 v[198:199], off
	s_mov_b32 m0, s2
	v_readlane_b32 s3, v255, 16
	s_mov_b32 s2, m0
	s_mov_b32 m0, s31
	s_nop 0
	global_load_lds_dwordx4 v[194:195], off
	s_mov_b32 m0, s2
	s_cmp_eq_u32 s22, 15
	s_mov_b32 s2, m0
	s_mov_b32 m0, s3
	s_nop 0
	global_load_lds_dwordx4 v[192:193], off
	s_mov_b32 m0, s2
	v_readlane_b32 s3, v255, 17
	s_mov_b32 s2, m0
	s_mov_b32 m0, s3
	s_nop 0
	global_load_lds_dwordx4 v[190:191], off
	s_mov_b32 m0, s2
	v_readlane_b32 s3, v255, 18
	s_mov_b32 s2, m0
	s_mov_b32 m0, s3
	s_nop 0
	global_load_lds_dwordx4 v[188:189], off
	s_mov_b32 m0, s2
	v_readlane_b32 s3, v255, 19
	s_mov_b32 s2, m0
	s_mov_b32 m0, s3
	s_nop 0
	global_load_lds_dwordx4 v[184:185], off
	s_mov_b32 m0, s2
	v_readlane_b32 s3, v255, 20
	s_mov_b32 s2, m0
	s_mov_b32 m0, s3
	s_nop 0
	global_load_lds_dwordx4 v[186:187], off
	s_mov_b32 m0, s2
	s_cbranch_scc1 .LBB0_427
	s_add_i32 s80, s23, -1
	s_lshl_b64 s[2:3], s[80:81], 14
	v_lshl_add_u64 v[2:3], v[180:181], 0, s[2:3]
	v_readlane_b32 s8, v255, 21
	s_mov_b32 s5, m0
	s_mov_b32 m0, s8
	s_nop 0
	global_load_lds_dwordx4 v[2:3], off
	s_mov_b32 m0, s5
	v_lshl_add_u64 v[2:3], v[2:3], 0, s[88:89]
	v_readlane_b32 s8, v255, 22
	s_mov_b32 s5, m0
	s_mov_b32 m0, s8
	s_nop 0
	global_load_lds_dwordx4 v[2:3], off
	s_mov_b32 m0, s5
	v_lshl_add_u64 v[2:3], v[182:183], 0, s[2:3]
	v_readlane_b32 s3, v255, 23
	s_mov_b32 s2, m0
	s_mov_b32 m0, s3
	s_nop 0
	global_load_lds_dwordx4 v[2:3], off
	s_mov_b32 m0, s2
	v_lshl_add_u64 v[2:3], v[2:3], 0, s[88:89]
	v_readlane_b32 s3, v255, 24
	s_mov_b32 s2, m0
	s_mov_b32 m0, s3
	s_nop 0
	global_load_lds_dwordx4 v[2:3], off
	s_mov_b32 m0, s2

.LBB0_451:
	s_setprio 0
	s_mov_b32 s95, 0
	v_mbcnt_lo_u32_b32 v0, -1, 0
	v_mbcnt_hi_u32_b32 v0, -1, v0
	v_readlane_b32 s2, v254, 2
	v_sub_u32_e32 v0, 0, v0
	v_mov_b32_e32 v95, 0xf0000
	v_cmp_eq_u32_e32 vcc, s2, v0
	s_and_saveexec_b64 s[2:3], vcc
	s_cbranch_execz .LBB0_456
	v_mov_b32_e32 v0, s69
	ds_read_b32 v0, v0
	v_readlane_b32 s5, v254, 32
	v_readlane_b32 s8, v254, 34
	v_mov_b32_e32 v95, 0xf0000
	s_waitcnt lgkmcnt(0)
	v_readfirstlane_b32 s4, v0
	s_and_b32 s5, s4, s5
	s_cmp_eq_u32 s5, 0
	v_readlane_b32 s5, v254, 31
	s_cselect_b32 s5, s5, 15
	s_and_b32 s8, s4, s8
	s_cmp_eq_u32 s8, 0
	v_readlane_b32 s8, v254, 33
	s_cselect_b32 s5, s8, s5
	v_readlane_b32 s8, v254, 36
	s_and_b32 s8, s4, s8
	s_cmp_eq_u32 s8, 0
	v_readlane_b32 s8, v254, 35
	s_cselect_b32 s5, s8, s5
	v_readlane_b32 s8, v254, 38
	s_and_b32 s8, s4, s8
	s_cmp_eq_u32 s8, 0
	v_readlane_b32 s8, v254, 37
	s_cselect_b32 s5, s8, s5
	v_readlane_b32 s8, v254, 40
	s_and_b32 s8, s4, s8
	s_cmp_eq_u32 s8, 0
	v_readlane_b32 s8, v254, 39
	s_cselect_b32 s5, s8, s5
	v_readlane_b32 s8, v254, 42
	s_and_b32 s8, s4, s8
	s_cmp_eq_u32 s8, 0
	v_readlane_b32 s8, v254, 41
	s_cselect_b32 s5, s8, s5
	v_readlane_b32 s8, v254, 44
	s_and_b32 s8, s4, s8
	s_cmp_eq_u32 s8, 0
	v_readlane_b32 s8, v254, 43
	s_cselect_b32 s5, s8, s5
	v_readlane_b32 s8, v254, 46
	s_and_b32 s8, s4, s8
	s_cmp_eq_u32 s8, 0
	v_readlane_b32 s8, v254, 45
	s_cselect_b32 s5, s8, s5
	s_bitcmp0_b32 s4, 8
	s_cselect_b32 s4, 8, 15
	s_cmp_eq_u32 s5, 15
	s_cselect_b32 s10, s4, s5
	s_cmp_eq_u32 s10, 15
	s_cbranch_scc1 .LBB0_456
	s_mov_b64 s[8:9], exec
	v_mbcnt_lo_u32_b32 v0, s8, 0
	v_mbcnt_hi_u32_b32 v0, s9, v0
	v_cmp_eq_u32_e32 vcc, 0, v0
	s_and_saveexec_b64 s[4:5], vcc
	s_cbranch_execz .LBB0_455
	s_lshl_b32 s11, s10, 6
	s_add_i32 s11, s11, 64
	s_cmp_lt_u32 s10, 8
	s_cselect_b32 s80, s11, 0
	s_lshl_b64 s[12:13], s[80:81], 2
	v_readlane_b32 s14, v254, 51
	v_readlane_b32 s15, v254, 52
	s_add_u32 s12, s14, s12
	s_addc_u32 s13, s15, s13
	s_bcnt1_i32_b64 s8, s[8:9]
	v_mov_b32_e32 v253, s8
	global_atomic_add v253, v1, v253, s[12:13] sc0
	s_mov_b32 s95, 1
